# speedup vs baseline: 1.0159x; 1.0159x over previous
; __device__ __forceinline__ void stg16f(void* p, float a, float b, float c, float d) { typedef float f32x4_ __attribute__((ext_vector_type(4))); const f32x4_ v = {a, b, c, d}; *(__attribute__((address_space(1))) f32x4_*)(p) = v; }
; __device__ __forceinline__ float4 ldg16f(const void* p) { typedef float f32x4_ __attribute__((ext_vector_type(4))); const f32x4_ v = *(const __attribute__((address_space(1))) f32x4_*)(p); return make_float4(v.x, v.y, v.z, v.w); }
; #define EPI_LOOP(...) _Pragma("unroll") for (int ai = 0; ai < 2; ++ai) _Pragma("unroll") for (int bj = 0; bj < 2; ++bj) \
;     _Pragma("unroll") for (int m = 0; m < 4; ++m) _Pragma("unroll") for (int n = 0; n < 2; ++n) { \
;       const int o = toff + (ai * HALF + m * 16) * ld + bj * HALF + n * 16; const f32x4 v = acc[ai][bj][m][n]; __VA_ARGS__ }
; template <class EPIF>
; __device__ __forceinline__ void gemm_stream(const u16* __restrict__ A, const u16* __restrict__ Bt, const int K, const int nM,
;                                             const int nN, const int loc, const int G, EPIF epif, u16* shm, const int wv) {
;     ...
;         float* d = (float*)ep.dst + (long)brow * ld + ccol;
;         const float* r = ep.res + (long)brow * ld + ccol;
;         EPI_LOOP({ const float4 rv = ldg16f(r + o); stg16f(d + o, rv.x + v[0], rv.y + v[1], rv.z + v[2], rv.w + v[3]); })
.LBB0_293:
	s_lshl_b64 s[8:9], s[24:25], 2
	s_lshl_b64 s[10:11], s[22:23], 2
	s_waitcnt vmcnt(0) lgkmcnt(0)
	v_lshl_add_u64 v[152:153], v[134:135], 0, s[8:9]
	v_lshl_add_u64 v[150:151], v[146:147], 0, s[8:9]
	v_lshl_add_u64 v[152:153], v[152:153], 0, s[10:11]
	v_lshl_add_u64 v[150:151], v[150:151], 0, s[10:11]
	s_lshl_b32 s8, s83, 4
	s_lshl_b32 s9, s83, 7
	s_mov_b32 s10, 0
	v_add_u32_e32 v182, s10, v148
	v_ashrrev_i32_e32 v183, 31, v182
	v_lshlrev_b64 v[182:183], 2, v[182:183]
	v_lshl_add_u64 v[174:175], v[152:153], 0, v[182:183]
	global_load_dwordx4 v[186:189], v[174:175], off
	global_load_dwordx4 v[190:193], v[174:175], off offset:64
	global_load_dwordx4 v[194:197], v[174:175], off offset:512
	global_load_dwordx4 v[198:201], v[174:175], off offset:576
	s_mul_i32 s10, s8, 1
	v_add_u32_e32 v182, s10, v148
	v_ashrrev_i32_e32 v183, 31, v182
	v_lshlrev_b64 v[182:183], 2, v[182:183]
	v_lshl_add_u64 v[174:175], v[152:153], 0, v[182:183]
	global_load_dwordx4 v[202:205], v[174:175], off
	global_load_dwordx4 v[206:209], v[174:175], off offset:64
	global_load_dwordx4 v[216:219], v[174:175], off offset:512
	global_load_dwordx4 v[220:223], v[174:175], off offset:576
	s_mov_b32 s10, 0
	v_add_u32_e32 v182, s10, v148
	v_ashrrev_i32_e32 v183, 31, v182
	v_lshlrev_b64 v[182:183], 2, v[182:183]
	v_lshl_add_u64 v[176:177], v[150:151], 0, v[182:183]
	s_mul_i32 s10, s8, 2
	v_add_u32_e32 v182, s10, v148
	v_ashrrev_i32_e32 v183, 31, v182
	v_lshlrev_b64 v[182:183], 2, v[182:183]
	v_lshl_add_u64 v[174:175], v[152:153], 0, v[182:183]
	s_waitcnt vmcnt(7)
	v_pk_add_f32 v[186:187], v[124:125], v[186:187]
	v_pk_add_f32 v[188:189], v[126:127], v[188:189]
	global_store_dwordx4 v[176:177], v[186:189], off
	global_load_dwordx4 v[186:189], v[174:175], off
	s_waitcnt vmcnt(8)
	v_pk_add_f32 v[190:191], v[120:121], v[190:191]
	v_pk_add_f32 v[192:193], v[122:123], v[192:193]
	global_store_dwordx4 v[176:177], v[190:193], off offset:64
	global_load_dwordx4 v[190:193], v[174:175], off offset:64
	s_waitcnt vmcnt(9)
	v_pk_add_f32 v[194:195], v[108:109], v[194:195]
	v_pk_add_f32 v[196:197], v[110:111], v[196:197]
	global_store_dwordx4 v[176:177], v[194:197], off offset:512
	global_load_dwordx4 v[194:197], v[174:175], off offset:512
	s_waitcnt vmcnt(10)
	v_pk_add_f32 v[198:199], v[104:105], v[198:199]
	v_pk_add_f32 v[200:201], v[106:107], v[200:201]
	global_store_dwordx4 v[176:177], v[198:201], off offset:576
	global_load_dwordx4 v[198:201], v[174:175], off offset:576
	s_mul_i32 s10, s8, 1
	v_add_u32_e32 v182, s10, v148
	v_ashrrev_i32_e32 v183, 31, v182
	v_lshlrev_b64 v[182:183], 2, v[182:183]
	v_lshl_add_u64 v[176:177], v[150:151], 0, v[182:183]
	s_mul_i32 s10, s8, 3
	v_add_u32_e32 v182, s10, v148
	v_ashrrev_i32_e32 v183, 31, v182
	v_lshlrev_b64 v[182:183], 2, v[182:183]
	v_lshl_add_u64 v[174:175], v[152:153], 0, v[182:183]
	s_waitcnt vmcnt(11)
	v_pk_add_f32 v[202:203], v[116:117], v[202:203]
	v_pk_add_f32 v[204:205], v[118:119], v[204:205]
	global_store_dwordx4 v[176:177], v[202:205], off
	global_load_dwordx4 v[202:205], v[174:175], off
	s_waitcnt vmcnt(12)
	v_pk_add_f32 v[206:207], v[112:113], v[206:207]
	v_pk_add_f32 v[208:209], v[114:115], v[208:209]
	global_store_dwordx4 v[176:177], v[206:209], off offset:64
	global_load_dwordx4 v[206:209], v[174:175], off offset:64
	s_waitcnt vmcnt(13)
	v_pk_add_f32 v[216:217], v[92:93], v[216:217]
	v_pk_add_f32 v[218:219], v[94:95], v[218:219]
	global_store_dwordx4 v[176:177], v[216:219], off offset:512
	global_load_dwordx4 v[216:219], v[174:175], off offset:512
	s_waitcnt vmcnt(14)
	v_pk_add_f32 v[220:221], v[88:89], v[220:221]
	v_pk_add_f32 v[222:223], v[90:91], v[222:223]
	global_store_dwordx4 v[176:177], v[220:223], off offset:576
	global_load_dwordx4 v[220:223], v[174:175], off offset:576
	s_mul_i32 s10, s8, 2
	v_add_u32_e32 v182, s10, v148
	v_ashrrev_i32_e32 v183, 31, v182
	v_lshlrev_b64 v[182:183], 2, v[182:183]
	v_lshl_add_u64 v[176:177], v[150:151], 0, v[182:183]
	s_mov_b32 s10, 0
	s_add_i32 s10, s10, s9
	v_add_u32_e32 v182, s10, v148
	v_ashrrev_i32_e32 v183, 31, v182
	v_lshlrev_b64 v[182:183], 2, v[182:183]
	v_lshl_add_u64 v[174:175], v[152:153], 0, v[182:183]
	s_waitcnt vmcnt(14)
	v_pk_add_f32 v[186:187], v[100:101], v[186:187]
	v_pk_add_f32 v[188:189], v[102:103], v[188:189]
	global_store_dwordx4 v[176:177], v[186:189], off
	global_load_dwordx4 v[186:189], v[174:175], off
	s_waitcnt vmcnt(14)
	v_pk_add_f32 v[190:191], v[96:97], v[190:191]
	v_pk_add_f32 v[192:193], v[98:99], v[192:193]
	global_store_dwordx4 v[176:177], v[190:193], off offset:64
	global_load_dwordx4 v[190:193], v[174:175], off offset:64
	s_waitcnt vmcnt(14)
	v_pk_add_f32 v[194:195], v[72:73], v[194:195]
	v_pk_add_f32 v[196:197], v[74:75], v[196:197]
	global_store_dwordx4 v[176:177], v[194:197], off offset:512
	global_load_dwordx4 v[194:197], v[174:175], off offset:512
	s_waitcnt vmcnt(14)
	v_pk_add_f32 v[198:199], v[64:65], v[198:199]
	v_pk_add_f32 v[200:201], v[66:67], v[200:201]
	global_store_dwordx4 v[176:177], v[198:201], off offset:576
	global_load_dwordx4 v[198:201], v[174:175], off offset:576
	s_mul_i32 s10, s8, 3
	v_add_u32_e32 v182, s10, v148
	v_ashrrev_i32_e32 v183, 31, v182
	v_lshlrev_b64 v[182:183], 2, v[182:183]
	v_lshl_add_u64 v[176:177], v[150:151], 0, v[182:183]
	s_mul_i32 s10, s8, 1
	s_add_i32 s10, s10, s9
	v_add_u32_e32 v182, s10, v148
	v_ashrrev_i32_e32 v183, 31, v182
	v_lshlrev_b64 v[182:183], 2, v[182:183]
	v_lshl_add_u64 v[174:175], v[152:153], 0, v[182:183]
	s_waitcnt vmcnt(14)
; __device__ __forceinline__ void stg16f(void* p, float a, float b, float c, float d) { typedef float f32x4_ __attribute__((ext_vector_type(4))); const f32x4_ v = {a, b, c, d}; *(__attribute__((address_space(1))) f32x4_*)(p) = v; }
; __device__ __forceinline__ float4 ldg16f(const void* p) { typedef float f32x4_ __attribute__((ext_vector_type(4))); const f32x4_ v = *(const __attribute__((address_space(1))) f32x4_*)(p); return make_float4(v.x, v.y, v.z, v.w); }
; #define EPI_LOOP(...) _Pragma("unroll") for (int ai = 0; ai < 2; ++ai) _Pragma("unroll") for (int bj = 0; bj < 2; ++bj) \
;     _Pragma("unroll") for (int m = 0; m < 4; ++m) _Pragma("unroll") for (int n = 0; n < 2; ++n) { \
;       const int o = toff + (ai * HALF + m * 16) * ld + bj * HALF + n * 16; const f32x4 v = acc[ai][bj][m][n]; __VA_ARGS__ }
; template <class EPIF>
; __device__ __forceinline__ void gemm_stream(const u16* __restrict__ A, const u16* __restrict__ Bt, const int K, const int nM,
;                                             const int nN, const int loc, const int G, EPIF epif, u16* shm, const int wv) {
;     ...
;         float* d = (float*)ep.dst + (long)brow * ld + ccol;
;         const float* r = ep.res + (long)brow * ld + ccol;
;         EPI_LOOP({ const float4 rv = ldg16f(r + o); stg16f(d + o, rv.x + v[0], rv.y + v[1], rv.z + v[2], rv.w + v[3]); })
	v_pk_add_f32 v[202:203], v[84:85], v[202:203]
	v_pk_add_f32 v[204:205], v[86:87], v[204:205]
	global_store_dwordx4 v[176:177], v[202:205], off
	global_load_dwordx4 v[202:205], v[174:175], off
	s_waitcnt vmcnt(14)
	v_pk_add_f32 v[206:207], v[80:81], v[206:207]
	v_pk_add_f32 v[208:209], v[82:83], v[208:209]
	global_store_dwordx4 v[176:177], v[206:209], off offset:64
	global_load_dwordx4 v[206:209], v[174:175], off offset:64
	s_waitcnt vmcnt(14)
	v_pk_add_f32 v[216:217], v[56:57], v[216:217]
	v_pk_add_f32 v[218:219], v[58:59], v[218:219]
	global_store_dwordx4 v[176:177], v[216:219], off offset:512
	global_load_dwordx4 v[216:219], v[174:175], off offset:512
	s_waitcnt vmcnt(14)
	v_pk_add_f32 v[220:221], v[48:49], v[220:221]
	v_pk_add_f32 v[222:223], v[50:51], v[222:223]
	global_store_dwordx4 v[176:177], v[220:223], off offset:576
	global_load_dwordx4 v[220:223], v[174:175], off offset:576
	s_mov_b32 s10, 0
	s_add_i32 s10, s10, s9
	v_add_u32_e32 v182, s10, v148
	v_ashrrev_i32_e32 v183, 31, v182
	v_lshlrev_b64 v[182:183], 2, v[182:183]
	v_lshl_add_u64 v[176:177], v[150:151], 0, v[182:183]
	s_mul_i32 s10, s8, 2
	s_add_i32 s10, s10, s9
	v_add_u32_e32 v182, s10, v148
	v_ashrrev_i32_e32 v183, 31, v182
	v_lshlrev_b64 v[182:183], 2, v[182:183]
	v_lshl_add_u64 v[174:175], v[152:153], 0, v[182:183]
	s_waitcnt vmcnt(14)
	v_pk_add_f32 v[186:187], v[76:77], v[186:187]
	v_pk_add_f32 v[188:189], v[78:79], v[188:189]
	global_store_dwordx4 v[176:177], v[186:189], off
	global_load_dwordx4 v[186:189], v[174:175], off
	s_waitcnt vmcnt(14)
	v_pk_add_f32 v[190:191], v[68:69], v[190:191]
	v_pk_add_f32 v[192:193], v[70:71], v[192:193]
	global_store_dwordx4 v[176:177], v[190:193], off offset:64
	global_load_dwordx4 v[190:193], v[174:175], off offset:64
	s_waitcnt vmcnt(14)
	v_pk_add_f32 v[194:195], v[36:37], v[194:195]
	v_pk_add_f32 v[196:197], v[38:39], v[196:197]
	global_store_dwordx4 v[176:177], v[194:197], off offset:512
	global_load_dwordx4 v[194:197], v[174:175], off offset:512
	s_waitcnt vmcnt(14)
	v_pk_add_f32 v[198:199], v[32:33], v[198:199]
	v_pk_add_f32 v[200:201], v[34:35], v[200:201]
	global_store_dwordx4 v[176:177], v[198:201], off offset:576
	global_load_dwordx4 v[198:201], v[174:175], off offset:576
	s_mul_i32 s10, s8, 1
	s_add_i32 s10, s10, s9
	v_add_u32_e32 v182, s10, v148
	v_ashrrev_i32_e32 v183, 31, v182
	v_lshlrev_b64 v[182:183], 2, v[182:183]
	v_lshl_add_u64 v[176:177], v[150:151], 0, v[182:183]
	s_mul_i32 s10, s8, 3
	s_add_i32 s10, s10, s9
	v_add_u32_e32 v182, s10, v148
	v_ashrrev_i32_e32 v183, 31, v182
	v_lshlrev_b64 v[182:183], 2, v[182:183]
	v_lshl_add_u64 v[174:175], v[152:153], 0, v[182:183]
	s_waitcnt vmcnt(14)
	v_pk_add_f32 v[202:203], v[60:61], v[202:203]
	v_pk_add_f32 v[204:205], v[62:63], v[204:205]
	global_store_dwordx4 v[176:177], v[202:205], off
	global_load_dwordx4 v[202:205], v[174:175], off
	s_waitcnt vmcnt(14)
	v_pk_add_f32 v[206:207], v[52:53], v[206:207]
	v_pk_add_f32 v[208:209], v[54:55], v[208:209]
	global_store_dwordx4 v[176:177], v[206:209], off offset:64
	global_load_dwordx4 v[206:209], v[174:175], off offset:64
	s_waitcnt vmcnt(14)
	v_pk_add_f32 v[216:217], v[20:21], v[216:217]
	v_pk_add_f32 v[218:219], v[22:23], v[218:219]
	global_store_dwordx4 v[176:177], v[216:219], off offset:512
	global_load_dwordx4 v[216:219], v[174:175], off offset:512
	s_waitcnt vmcnt(14)
	v_pk_add_f32 v[220:221], v[16:17], v[220:221]
	v_pk_add_f32 v[222:223], v[18:19], v[222:223]
	global_store_dwordx4 v[176:177], v[220:223], off offset:576
	global_load_dwordx4 v[220:223], v[174:175], off offset:576
	s_mul_i32 s10, s8, 2
	s_add_i32 s10, s10, s9
	v_add_u32_e32 v182, s10, v148
	v_ashrrev_i32_e32 v183, 31, v182
	v_lshlrev_b64 v[182:183], 2, v[182:183]
	v_lshl_add_u64 v[176:177], v[150:151], 0, v[182:183]
	s_waitcnt vmcnt(14)
	v_pk_add_f32 v[186:187], v[44:45], v[186:187]
	v_pk_add_f32 v[188:189], v[46:47], v[188:189]
	global_store_dwordx4 v[176:177], v[186:189], off
	s_waitcnt vmcnt(13)
	v_pk_add_f32 v[190:191], v[40:41], v[190:191]
	v_pk_add_f32 v[192:193], v[42:43], v[192:193]
	global_store_dwordx4 v[176:177], v[190:193], off offset:64
	s_waitcnt vmcnt(12)
	v_pk_add_f32 v[194:195], v[12:13], v[194:195]
	v_pk_add_f32 v[196:197], v[14:15], v[196:197]
	global_store_dwordx4 v[176:177], v[194:197], off offset:512
	s_waitcnt vmcnt(11)
	v_pk_add_f32 v[198:199], v[8:9], v[198:199]
	v_pk_add_f32 v[200:201], v[10:11], v[200:201]
	global_store_dwordx4 v[176:177], v[198:201], off offset:576
	s_mul_i32 s10, s8, 3
	s_add_i32 s10, s10, s9
	v_add_u32_e32 v182, s10, v148
	v_ashrrev_i32_e32 v183, 31, v182
	v_lshlrev_b64 v[182:183], 2, v[182:183]
	v_lshl_add_u64 v[176:177], v[150:151], 0, v[182:183]
	s_waitcnt vmcnt(10)
	v_pk_add_f32 v[202:203], v[28:29], v[202:203]
	v_pk_add_f32 v[204:205], v[30:31], v[204:205]
	global_store_dwordx4 v[176:177], v[202:205], off
	s_waitcnt vmcnt(9)
	v_pk_add_f32 v[206:207], v[24:25], v[206:207]
	v_pk_add_f32 v[208:209], v[26:27], v[208:209]
	global_store_dwordx4 v[176:177], v[206:209], off offset:64
	s_waitcnt vmcnt(8)
	v_pk_add_f32 v[216:217], v[4:5], v[216:217]
	v_pk_add_f32 v[218:219], v[6:7], v[218:219]
	global_store_dwordx4 v[176:177], v[216:219], off offset:512
	s_waitcnt vmcnt(7)
	v_pk_add_f32 v[220:221], v[0:1], v[220:221]
	v_pk_add_f32 v[222:223], v[2:3], v[222:223]
	global_store_dwordx4 v[176:177], v[220:223], off offset:576
	s_cbranch_execnz .LBB0_185
